# rebalance sample-scan items across non-scan WGs (heavy WGs with extra sample-attention skip their 2 sample scans; 40 other WGs take them)
# baseline (speedup 1.0000x reference)
; __device__ __forceinline__ bool phase_mixers(const Args& A, const Ctx& C0, int l, int unmask) {
;     ...
;     if (C.G >= N_PSCAN + 64) {
;         if (C.bid < N_PSCAN) mixer_item(A, C, l, C.bid, unmask);
;         else {
;             const int no = C.G - N_PSCAN;
;             for (int it = N_PSCAN + (C.bid - N_PSCAN); it < NI; it += no) mixer_item(A, C, l, it, unmask);
.LBB0_688:
	s_and_b64 vcc, exec, s[0:1]
	s_cbranch_vccz .LBB0_1181
	s_add_i32 s73, s76, 0xffffff80
	s_cmpk_gt_u32 s72, 0x997
	s_cbranch_scc1 .LBB0_1163
	s_bitcmp1_b32 s72, 0
	s_cselect_b64 s[54:55], -1, 0
	s_bitcmp1_b32 s76, 0
	s_cselect_b64 s[48:49], -1, 0
	v_writelane_b32 v255, s48, 56
	s_mov_b32 s74, s72
	s_add_i32 s98, s72, 0xffffff80
	s_mov_b32 s99, 0
	s_cmp_lt_u32 s98, 64
	s_cselect_b32 s99, 0xffffff80, s99
	s_cmp_lt_u32 s98, 24
	s_cselect_b32 s99, 0x80, s99
	s_cmp_lt_u32 s98, 16
	s_cselect_b32 s99, 0x100, s99
	s_add_i32 s74, s72, s99
	s_nop 0
	v_writelane_b32 v255, s49, 57
	s_branch .LBB0_694

; __device__ __forceinline__ bool phase_mixers(const Args& A, const Ctx& C0, int l, int unmask) {
;     ...
;             for (int it = N_PSCAN + (C.bid - N_PSCAN); it < NI; it += no) mixer_item(A, C, l, it, unmask);
.LBB0_692:
	s_sub_i32 s74, s74, s99
	s_waitcnt vmcnt(0) lgkmcnt(0)
	s_barrier

; #define SCAN_BAR() asm volatile("s_barrier" ::: "memory")
; __device__ __forceinline__ void scan_unit(const Ctx& C0, const float* scn, int T, int quarter, const float* S0, float* Sout, unsigned char* obase, int mode) {
;     Ctx C = C0; C.tid = threadIdx.x; asm volatile("" : "+v"(C.tid)); asm volatile("" : "+s"(C.G), "+s"(C.bid)); C.lane = C.tid & 63; C.wave = __builtin_amdgcn_readfirstlane(C.tid >> 6);
;     constexpr int SLOT_B = 32 * 1536;
;     const bool comp = C.wave < 4;
;     const int q = C.lane & 15, rr = C.lane >> 4, rl = (C.wave & 3) * 4 + rr, irow = quarter * 16 + rl;
;     const int nch = T / 32;
;     __syncthreads();
;     if (!comp) {
;         const int lw = C.wave - 4;
;         unsigned goff[12];
; #pragma unroll
;         for (int i = 0; i < 12; ++i) { const int x = (lw * 12 + i) * 1024 + C.lane * 16; goff[i] = (unsigned)((x / 1536) * 12288 + (x % 1536)); }
;         const unsigned char* sb = (const unsigned char*)scn;
;     ...
;         if (mode != 1) SCAN_ISSUE(0);
;         asm volatile("s_waitcnt vmcnt(0)" ::: "memory");
;         SCAN_BAR();
;         for (int k = 0; k < nch; ++k) {
;             if (mode != 1) SCAN_ISSUE(k + 1);
; __device__ __forceinline__ void mixer_item(const Args& A, const Ctx& C, int l, int it, int unmask) {
;     ...
;         const bool smp = it >= N_PSCAN; const int i2 = smp ? it - N_PSCAN : it;
;         int b, hd, qd;
;         if (smp) { b = i2 >> 5; hd = (i2 >> 2) & 7; qd = i2 & 3; }
;         else { const int xg = i2 & 7, idx = i2 >> 3, pair = xg * 4 + (idx >> 2); qd = idx & 3; b = pair >> 3; hd = pair & 7; }
;         const size_t row0 = smp ? (size_t)MP + b * DECS : (size_t)b * SEQ;
;         const float* S0 = smp ? A.in[I_SWKV] + ((size_t)(l * DECB + b) * 8 + hd) * 4096 : nullptr;
;         float* So = smp ? A.out + O_WKVS + ((size_t)(l * DECB + b) * 8 + hd) * 4096 : A.out + O_WKVP + ((size_t)(l * BATCH + b) * 8 + hd) * 4096;
;         if (unmask & UN_MASK & 1) scan_unit(C, SCN + row0 * 3072 + hd * 384, smp ? DECS : SEQ, qd, S0, So, Ub + row0 * UPITCH_B + UXC_B + (hd * 64 + qd * 16) * 4, (unmask >> 4) & 3);
.LBB0_774:
	s_movk_i32 s99, 0x58
	s_cmp_lt_u32 s74, 56
	s_cselect_b32 s99, 0xd8, s99
	s_cmp_lt_u32 s74, 40
	s_cselect_b32 s99, 0x68, s99
	s_cmpk_lt_u32 s74, 0x80
	s_cselect_b32 s99, s99, 0
	s_add_i32 s74, s74, s99
	v_mov_b32_e32 v0, v185
	s_mov_b32 s0, s72
	s_mov_b32 s1, s76
	s_add_i32 s2, s74, 0xffffff80
	s_and_b32 s9, s2, 0xffffffe0
	v_readfirstlane_b32 s0, v0
	s_bfe_u32 s8, s74, 0x30002
	s_add_i32 s9, s9, 0x8000
	s_ashr_i32 s3, s0, 6
	v_and_b32_e32 v2, 63, v0
	s_cmp_lt_i32 s3, 4
	s_mov_b64 s[0:1], -1
	s_barrier
	s_cbranch_scc1 .LBB0_776
	s_mul_i32 s1, s9, 0x3000
	s_mul_hi_u32 s0, s9, 0x3000
	s_add_u32 s1, s50, s1
	s_addc_u32 s0, s51, s0
	s_mul_i32 s10, s8, 0x600
	s_add_u32 s1, s1, s10
	s_addc_u32 s10, s0, 0
	s_add_u32 s0, s1, 0x256d7900
	s_addc_u32 s1, s10, 0
	s_mul_i32 s10, s3, 0x3000
	s_waitcnt lgkmcnt(0)
	v_lshlrev_b32_e32 v3, 4, v2
	s_add_i32 s11, s10, 0xffff4000
	v_or_b32_e32 v4, s11, v3
	s_mov_b32 s26, 0xaaaaaaab
	v_mul_hi_u32 v5, v4, s26
	v_lshrrev_b32_e32 v5, 10, v5
	v_mul_u32_u24_e32 v6, 0x3000, v5
	v_mul_u32_u24_e32 v5, 0x600, v5
	s_add_i32 s12, s10, 0xffff4400
	v_sub_u32_e32 v4, v4, v5
	v_or_b32_e32 v5, s12, v3
	v_or_b32_e32 v4, v6, v4
	v_mul_hi_u32 v6, v5, s26
	v_lshrrev_b32_e32 v6, 10, v6
	v_mul_u32_u24_e32 v7, 0x3000, v6
	v_mul_u32_u24_e32 v6, 0x600, v6
	s_add_i32 s13, s10, 0xffff4800
	v_sub_u32_e32 v5, v5, v6
	v_or_b32_e32 v6, s13, v3
	v_or_b32_e32 v5, v7, v5
	v_mul_hi_u32 v7, v6, s26
	v_lshrrev_b32_e32 v7, 10, v7
	v_mul_u32_u24_e32 v8, 0x3000, v7
	v_mul_u32_u24_e32 v7, 0x600, v7
	s_add_i32 s14, s10, 0xffff4c00
	v_sub_u32_e32 v6, v6, v7
	v_or_b32_e32 v7, s14, v3
	v_or_b32_e32 v6, v8, v6
	v_mul_hi_u32 v8, v7, s26
	v_lshrrev_b32_e32 v8, 10, v8
	v_mul_u32_u24_e32 v9, 0x3000, v8
	v_mul_u32_u24_e32 v8, 0x600, v8
	s_add_i32 s15, s10, 0xffff5000
	v_sub_u32_e32 v7, v7, v8
	v_or_b32_e32 v8, s15, v3
	v_or_b32_e32 v7, v9, v7
	v_mul_hi_u32 v9, v8, s26
	v_lshrrev_b32_e32 v9, 10, v9
	v_mul_u32_u24_e32 v10, 0x3000, v9
	v_mul_u32_u24_e32 v9, 0x600, v9
	s_add_i32 s16, s10, 0xffff5400
	v_sub_u32_e32 v8, v8, v9
	v_or_b32_e32 v9, s16, v3
	v_or_b32_e32 v8, v10, v8
	v_mul_hi_u32 v10, v9, s26
	v_lshrrev_b32_e32 v10, 10, v10
	v_mul_u32_u24_e32 v11, 0x3000, v10
	v_mul_u32_u24_e32 v10, 0x600, v10
	s_add_i32 s18, s10, 0xffff5800
	v_sub_u32_e32 v9, v9, v10
	v_or_b32_e32 v10, s18, v3
	v_or_b32_e32 v9, v11, v9
	v_mul_hi_u32 v11, v10, s26
	v_lshrrev_b32_e32 v11, 10, v11
	v_mul_u32_u24_e32 v12, 0x3000, v11
	v_mul_u32_u24_e32 v11, 0x600, v11
	s_add_i32 s19, s10, 0xffff5c00
	v_sub_u32_e32 v10, v10, v11
	v_or_b32_e32 v11, s19, v3
	v_or_b32_e32 v10, v12, v10
	v_mul_hi_u32 v12, v11, s26
	v_lshrrev_b32_e32 v12, 10, v12
	v_mul_u32_u24_e32 v13, 0x3000, v12
	v_mul_u32_u24_e32 v12, 0x600, v12
	s_add_i32 s24, s10, 0xffff6000
	v_sub_u32_e32 v11, v11, v12
	v_or_b32_e32 v12, s24, v3
	v_or_b32_e32 v11, v13, v11
	v_mul_hi_u32 v13, v12, s26
	v_lshrrev_b32_e32 v13, 10, v13
	v_mul_u32_u24_e32 v14, 0x3000, v13
	v_mul_u32_u24_e32 v13, 0x600, v13
	s_add_i32 s25, s10, 0xffff6400
	v_sub_u32_e32 v12, v12, v13
	v_or_b32_e32 v13, s25, v3
	v_or_b32_e32 v12, v14, v12
	v_mul_hi_u32 v14, v13, s26
	s_add_i32 m0, s11, 0
	v_lshrrev_b32_e32 v14, 10, v14
	global_load_lds_dwordx4 v4, s[0:1]
	s_add_i32 m0, s12, 0
	v_mul_u32_u24_e32 v15, 0x3000, v14
	v_mul_u32_u24_e32 v14, 0x600, v14
	s_add_i32 s30, s10, 0xffff6800
	global_load_lds_dwordx4 v5, s[0:1]
	s_add_i32 m0, s13, 0
	v_sub_u32_e32 v13, v13, v14
	v_or_b32_e32 v14, s30, v3
	global_load_lds_dwordx4 v6, s[0:1]
	s_add_i32 m0, s14, 0
	v_or_b32_e32 v13, v15, v13
	v_mul_hi_u32 v15, v14, s26
	global_load_lds_dwordx4 v7, s[0:1]
	s_add_i32 m0, s15, 0
	v_lshrrev_b32_e32 v15, 10, v15
	s_add_i32 s31, s10, 0xffff6c00
	global_load_lds_dwordx4 v8, s[0:1]
	s_add_i32 m0, s16, 0
	v_mul_u32_u24_e32 v16, 0x3000, v15
	v_mul_u32_u24_e32 v15, 0x600, v15
	v_or_b32_e32 v3, s31, v3
	global_load_lds_dwordx4 v9, s[0:1]
	s_add_i32 m0, s18, 0
	v_sub_u32_e32 v14, v14, v15
	v_mul_hi_u32 v15, v3, s26
	global_load_lds_dwordx4 v10, s[0:1]
	s_add_i32 m0, s19, 0
	v_lshrrev_b32_e32 v15, 10, v15
	global_load_lds_dwordx4 v11, s[0:1]
	s_add_i32 m0, s24, 0
	v_or_b32_e32 v14, v16, v14
	v_mul_u32_u24_e32 v16, 0x3000, v15
	v_mul_u32_u24_e32 v15, 0x600, v15
	global_load_lds_dwordx4 v12, s[0:1]
	s_add_i32 m0, s25, 0
	v_sub_u32_e32 v3, v3, v15
	global_load_lds_dwordx4 v13, s[0:1]
	s_add_i32 m0, s30, 0
	v_or_b32_e32 v3, v16, v3
	global_load_lds_dwordx4 v14, s[0:1]
	s_add_i32 m0, s31, 0
	s_add_i32 s10, s10, 0
	global_load_lds_dwordx4 v3, s[0:1]
	s_waitcnt vmcnt(0)
	s_barrier
	s_mov_b32 m0, s10
	s_nop 0
	global_load_lds_dwordx4 v4, s[0:1]
	s_add_i32 m0, s10, 0x400
	s_nop 0
	global_load_lds_dwordx4 v5, s[0:1]
	s_add_i32 m0, s10, 0x800
	s_nop 0
	global_load_lds_dwordx4 v6, s[0:1]
	s_add_i32 m0, s10, 0xc00
	s_nop 0
	global_load_lds_dwordx4 v7, s[0:1]
	s_add_i32 m0, s10, 0x1000
	s_nop 0
	global_load_lds_dwordx4 v8, s[0:1]
	s_add_i32 m0, s10, 0x1400
	s_nop 0
	global_load_lds_dwordx4 v9, s[0:1]
	s_add_i32 m0, s10, 0x1800
	s_nop 0
	global_load_lds_dwordx4 v10, s[0:1]
	s_add_i32 m0, s10, 0x1c00
	s_nop 0
	global_load_lds_dwordx4 v11, s[0:1]
	s_add_i32 m0, s10, 0x2000
	s_nop 0
	global_load_lds_dwordx4 v12, s[0:1]
	s_add_i32 m0, s10, 0x2400
	s_nop 0
	global_load_lds_dwordx4 v13, s[0:1]
	s_add_i32 m0, s10, 0x2800
	s_nop 0
	global_load_lds_dwordx4 v14, s[0:1]
	s_add_i32 m0, s10, 0x2c00
	s_nop 0
	global_load_lds_dwordx4 v3, s[0:1]
	s_waitcnt vmcnt(0)
	s_barrier
	s_mov_b64 s[0:1], 0
